# also deferred: w_out/w_pg/w_pp bf16 transposes moved from the prologue into the barrier wait after in-proj (hand-written 64x32 block transposer on waves 1-7)
# speedup vs baseline: 1.0273x; 1.0015x over previous
; __device__ __forceinline__ void p0_phase(LAS unsigned char* lds, const Args& a, const int w0) {
;     ...
;     for (int it = gw; it < I_IN + 2 * I_SQ + I_PP; it += NGW) {
;         int r = it;
;         if (r < I_IN) { const int L = r / (52 * 16), q = r % (52 * 16), nb = q % 52, kb = q / 52;
;             tr_item64(a.in[8] + (size_t)L * DM * INW, INW, DM, win_src_col(2 * nb), win_src_col(2 * nb + 1), a.in[7] + L * DM, (bf16_t*)(ws + WS_WIN) + (size_t)L * INW * DM, nb * 64, kb * 64, scr, lane); continue; }
;         r -= I_IN;
;         if (r < 2 * I_SQ) { const int which = r / I_SQ; r %= I_SQ; const int L = r / 256, q = r % 256, nb = q & 15, kb = q >> 4;
;             tr_item64(a.in[which ? 12 : 11] + (size_t)L * DM * DM, DM, DM, nb * 64, nb * 64 + 32, nullptr, (bf16_t*)(ws + (which ? WS_WPG : WS_WOUT)) + (size_t)L * DM * DM, nb * 64, kb * 64, scr, lane); continue; }
.LBB0_19:
	s_or_b64 exec, exec, s[4:5]
	v_mbcnt_lo_u32_b32 v2, -1, 0
	v_mbcnt_hi_u32_b32 v2, -1, v2
	v_writelane_b32 v255, s33, 3
	v_add_u32_e32 v41, s33, v2
	s_lshl_b32 s4, s46, 3
	v_readfirstlane_b32 s3, v41
	s_ashr_i32 s3, s3, 6
	v_and_b32_e32 v38, 63, v2
	v_writelane_b32 v255, s4, 4
	s_add_i32 s28, s3, s4
	s_lshl_b32 s42, s24, 3
	s_cmpk_gt_i32 s28, 0xcff
	v_lshlrev_b32_e32 v0, 3, v38
	v_and_b32_e32 v40, 31, v2
	v_writelane_b32 v255, s42, 5
	s_cbranch_scc1 .LBB0_130
	s_mulk_i32 s3, 0x4100
	s_add_i32 s4, s3, 0
	s_add_u32 s3, s26, 0x2c00000
	s_addc_u32 s29, s27, 0
	s_add_u32 s33, s26, 0x200000
	v_lshrrev_b32_e32 v39, 3, v38
	v_and_b32_e32 v4, 56, v0
	s_addc_u32 s44, s27, 0
	v_mul_u32_u24_e32 v5, 0x104, v4
	v_lshlrev_b32_e32 v6, 2, v39
	s_cmp_lg_u64 s[16:17], 0
	v_lshl_add_u32 v1, v38, 2, s4
	v_add3_u32 v42, s4, v5, v6
	s_cselect_b64 s[34:35], -1, 0
	s_lshl_b32 s4, s28, 12
	v_mov_b32_e32 v3, 0
	v_or_b32_e32 v43, 8, v39
	v_or_b32_e32 v44, 16, v39
	v_or_b32_e32 v45, 24, v39
	v_or_b32_e32 v46, 32, v39
	v_or_b32_e32 v47, 40, v39
	v_or_b32_e32 v48, 48, v39
	v_or_b32_e32 v49, 56, v39
	v_and_b32_e32 v50, 31, v2
	s_lshl_b32 s45, s28, 6
	s_lshl_b32 s47, s42, 6
	s_lshl_b32 s48, s28, 2
	s_lshl_b32 s49, s42, 2
	s_add_i32 s50, s4, 0xff300000
	s_lshl_b32 s51, s42, 12
	s_movk_i32 s52, 0x2000
	s_movk_i32 s53, 0x4000
	s_movk_i32 s54, 0x6000
	s_mov_b32 s55, 0x8000
	s_mov_b32 s56, 0xa000
	s_mov_b32 s57, 0xc000
	s_mov_b32 s58, 0xe000
	s_mov_b32 s59, 0x10000
	s_mov_b32 s60, 0x12000
	s_mov_b32 s61, 0x14000
	s_mov_b32 s62, 0x16000
	s_mov_b32 s63, 0x18000
	s_mov_b32 s64, 0x1a000
	s_mov_b32 s65, 0x1c000
	s_mov_b32 s66, 0x1e000
	s_mov_b32 s67, 0x20000
	s_mov_b32 s68, 0x22000
	s_mov_b32 s69, 0x24000
	s_mov_b32 s70, 0x26000
	s_mov_b32 s71, 0x28000
	s_mov_b32 s72, 0x2a000
	s_mov_b32 s73, 0x2c000
	s_mov_b32 s74, 0x2e000
	s_mov_b32 s75, 0x30000
	s_mov_b32 s76, 0x32000
	s_mov_b32 s77, 0x34000
	s_mov_b32 s78, 0x36000
	s_mov_b32 s79, 0x38000
	s_mov_b32 s80, 0x3a000
	s_mov_b32 s81, 0x3c000
	s_mov_b32 s82, 0x3e000
	s_mov_b32 s83, 0x3f000
	s_movk_i32 s84, 0x700
	s_movk_i32 s85, 0x500
	v_add_u32_e32 v51, 0x400, v1
	v_add_u32_e32 v52, 0x800, v1
	v_add_u32_e32 v53, 0xc00, v1
	v_add_u32_e32 v54, 0x1000, v1
	v_add_u32_e32 v55, 0x1400, v1
	v_add_u32_e32 v56, 0x1800, v1
	v_add_u32_e32 v57, 0x1c00, v1
	v_add_u32_e32 v58, 0x2000, v1
	v_add_u32_e32 v59, 0x2400, v1
	v_add_u32_e32 v60, 0x2800, v1
	v_add_u32_e32 v61, 0x2c00, v1
	v_add_u32_e32 v62, 0x3000, v1
	v_add_u32_e32 v63, 0x3400, v1
	v_add_u32_e32 v64, 0x3800, v1
	v_add_u32_e32 v65, 0x3c00, v1
	v_lshlrev_b32_e32 v2, 1, v4
	v_add_u32_e32 v66, 0x400, v42
	v_mov_b32_e32 v67, 0x3400
	s_mov_b32 s86, 0xc6000
	s_mov_b32 s87, 0xc9000
	s_mov_b32 s88, s28
	s_mov_b32 s37, 0
	v_cmp_gt_u32_e64 s[6:7], 32, v38
	s_branch .LBB0_23

; __device__ __forceinline__ void p0_phase(LAS unsigned char* lds, const Args& a, const int w0) {
;     ...
;     for (int it = gw; it < I_IN + 2 * I_SQ + I_PP; it += NGW) {
.LBB0_22:
	s_add_i32 s88, s88, s42
	s_add_i32 s45, s45, s47
	s_add_i32 s48, s48, s49
	s_add_i32 s50, s50, s51
	s_cmpk_gt_i32 s88, 0xcff
	s_cbranch_scc1 .LBB0_130

; #define LAS __attribute__((address_space(3)))
; template <class T, class P> __device__ __forceinline__ T gld_nt(P p) { return __builtin_nontemporal_load((GAS const T*)p); }
; __device__ __forceinline__ unsigned pk2(float lo, float hi) { return pg8::cvt_pk_bf16(lo, hi); }
; __device__ __forceinline__ void tr_item64(const float* W, int N, int K, int src_a, int src_b, const float* g, bf16_t* WT, int dst_row0, int k0, LAS float* scr, int lane) {
;     const int sc = (lane < 32 ? src_a : src_b) + (lane & 31);
;     float v[64];
; #pragma unroll
;     for (int kk = 0; kk < 64; ++kk) v[kk] = gld_nt<float>(W + (size_t)(k0 + kk) * N + sc);
; #pragma unroll
;     for (int kk = 0; kk < 64; ++kk) scr[kk * 65 + lane] = g ? v[kk] * gld<float>(g + k0 + kk) : v[kk];
;     asm volatile("s_waitcnt lgkmcnt(0)" ::: "memory");
;     const int c = lane & 7;
; #pragma unroll
;     for (int j = 0; j < 8; ++j) { const int n = (lane >> 3) + 8 * j; const LAS float* sp = scr + (8 * c) * 65 + n;
;         u32x4 o; o.x = pk2(sp[0 * 65], sp[1 * 65]); o.y = pk2(sp[2 * 65], sp[3 * 65]); o.z = pk2(sp[4 * 65], sp[5 * 65]); o.w = pk2(sp[6 * 65], sp[7 * 65]);
;         gst<u32x4>(WT + (size_t)(dst_row0 + n) * K + k0 + 8 * c, o); }
; __device__ __forceinline__ void p0_phase(LAS unsigned char* lds, const Args& a, const int w0) {
;     ...
;         { const int L = r / 64, q = r % 64, nb = q & 15, kb = q >> 4;
;             tr_item64(a.in[13] + (size_t)L * PLE * DM, DM, PLE, nb * 64, nb * 64 + 32, nullptr, (bf16_t*)(ws + WS_WPP) + (size_t)L * DM * PLE, nb * 64, kb * 64, scr, lane); }
.LBB0_130:
	s_cmp_gt_u32 s28, 127
	s_cbranch_scc1 .Ldw_p0_end
	s_load_dwordx2 s[4:5], s[0:1], 0x68
	s_load_dwordx2 s[8:9], s[0:1], 0x80
	s_mov_b32 s16, s28
	v_mbcnt_lo_u32_b32 v116, -1, 0
	v_mbcnt_hi_u32_b32 v116, -1, v116
	s_waitcnt lgkmcnt(0)
	s_add_u32 s8, s8, 0x2c00000
	s_addc_u32 s9, s9, 0
	s_and_b32 s6, s16, 15
	s_lshr_b32 s7, s16, 4
	s_lshl_b32 s7, s7, 17
	s_add_u32 s4, s4, s7
	s_addc_u32 s5, s5, 0
	s_lshl_b32 s7, s6, 8
	s_add_u32 s4, s4, s7
	s_addc_u32 s5, s5, 0
	s_lshl_b32 s6, s6, 15
	s_add_u32 s8, s8, s6
	s_addc_u32 s9, s9, 0
	s_lshr_b32 s7, s16, 4
	s_lshl_b32 s7, s7, 6
	s_add_u32 s8, s8, s7
	s_addc_u32 s9, s9, 0
	v_lshlrev_b32_e32 v108, 2, v116
	v_lshlrev_b32_e32 v109, 9, v116
	global_load_dword v60, v108, s[4:5] nt
	s_add_u32 s4, s4, 0x1000
	s_addc_u32 s5, s5, 0
	global_load_dword v61, v108, s[4:5] nt
	s_add_u32 s4, s4, 0x1000
	s_addc_u32 s5, s5, 0
	global_load_dword v62, v108, s[4:5] nt
	s_add_u32 s4, s4, 0x1000
	s_addc_u32 s5, s5, 0
	global_load_dword v63, v108, s[4:5] nt
	s_add_u32 s4, s4, 0x1000
	s_addc_u32 s5, s5, 0
	global_load_dword v64, v108, s[4:5] nt
	s_add_u32 s4, s4, 0x1000
	s_addc_u32 s5, s5, 0
	global_load_dword v65, v108, s[4:5] nt
	s_add_u32 s4, s4, 0x1000
	s_addc_u32 s5, s5, 0
	global_load_dword v66, v108, s[4:5] nt
	s_add_u32 s4, s4, 0x1000
	s_addc_u32 s5, s5, 0
	global_load_dword v67, v108, s[4:5] nt
	s_add_u32 s4, s4, 0x1000
	s_addc_u32 s5, s5, 0
	global_load_dword v68, v108, s[4:5] nt
	s_add_u32 s4, s4, 0x1000
	s_addc_u32 s5, s5, 0
	global_load_dword v69, v108, s[4:5] nt
	s_add_u32 s4, s4, 0x1000
	s_addc_u32 s5, s5, 0
	global_load_dword v70, v108, s[4:5] nt
	s_add_u32 s4, s4, 0x1000
	s_addc_u32 s5, s5, 0
	global_load_dword v71, v108, s[4:5] nt
	s_add_u32 s4, s4, 0x1000
	s_addc_u32 s5, s5, 0
	global_load_dword v72, v108, s[4:5] nt
	s_add_u32 s4, s4, 0x1000
	s_addc_u32 s5, s5, 0
	global_load_dword v73, v108, s[4:5] nt
	s_add_u32 s4, s4, 0x1000
	s_addc_u32 s5, s5, 0
	global_load_dword v74, v108, s[4:5] nt
	s_add_u32 s4, s4, 0x1000
	s_addc_u32 s5, s5, 0
	global_load_dword v75, v108, s[4:5] nt
	s_add_u32 s4, s4, 0x1000
	s_addc_u32 s5, s5, 0
	global_load_dword v76, v108, s[4:5] nt
	s_add_u32 s4, s4, 0x1000
	s_addc_u32 s5, s5, 0
	global_load_dword v77, v108, s[4:5] nt
	s_add_u32 s4, s4, 0x1000
	s_addc_u32 s5, s5, 0
	global_load_dword v78, v108, s[4:5] nt
	s_add_u32 s4, s4, 0x1000
	s_addc_u32 s5, s5, 0
	global_load_dword v79, v108, s[4:5] nt
	s_add_u32 s4, s4, 0x1000
	s_addc_u32 s5, s5, 0
	global_load_dword v80, v108, s[4:5] nt
	s_add_u32 s4, s4, 0x1000
	s_addc_u32 s5, s5, 0
	global_load_dword v81, v108, s[4:5] nt
	s_add_u32 s4, s4, 0x1000
	s_addc_u32 s5, s5, 0
	global_load_dword v82, v108, s[4:5] nt
	s_add_u32 s4, s4, 0x1000
	s_addc_u32 s5, s5, 0
	global_load_dword v83, v108, s[4:5] nt
	s_add_u32 s4, s4, 0x1000
	s_addc_u32 s5, s5, 0
	global_load_dword v84, v108, s[4:5] nt
	s_add_u32 s4, s4, 0x1000
	s_addc_u32 s5, s5, 0
	global_load_dword v85, v108, s[4:5] nt
	s_add_u32 s4, s4, 0x1000
	s_addc_u32 s5, s5, 0
	global_load_dword v86, v108, s[4:5] nt
	s_add_u32 s4, s4, 0x1000
	s_addc_u32 s5, s5, 0
	global_load_dword v87, v108, s[4:5] nt
	s_add_u32 s4, s4, 0x1000
	s_addc_u32 s5, s5, 0
	global_load_dword v88, v108, s[4:5] nt
	s_add_u32 s4, s4, 0x1000
	s_addc_u32 s5, s5, 0
	global_load_dword v89, v108, s[4:5] nt
	s_add_u32 s4, s4, 0x1000
	s_addc_u32 s5, s5, 0
	global_load_dword v90, v108, s[4:5] nt
	s_add_u32 s4, s4, 0x1000
	s_addc_u32 s5, s5, 0
	global_load_dword v91, v108, s[4:5] nt
	s_waitcnt vmcnt(24)
	v_cvt_pk_bf16_f32 v92, v60, v61
	v_cvt_pk_bf16_f32 v93, v62, v63
	v_cvt_pk_bf16_f32 v94, v64, v65
	v_cvt_pk_bf16_f32 v95, v66, v67
	s_waitcnt vmcnt(16)
	v_cvt_pk_bf16_f32 v96, v68, v69
	v_cvt_pk_bf16_f32 v97, v70, v71
	v_cvt_pk_bf16_f32 v98, v72, v73
	v_cvt_pk_bf16_f32 v99, v74, v75
	s_waitcnt vmcnt(8)
	v_cvt_pk_bf16_f32 v100, v76, v77
	v_cvt_pk_bf16_f32 v101, v78, v79
	v_cvt_pk_bf16_f32 v102, v80, v81
	v_cvt_pk_bf16_f32 v103, v82, v83
	s_waitcnt vmcnt(0)
	v_cvt_pk_bf16_f32 v104, v84, v85
	v_cvt_pk_bf16_f32 v105, v86, v87
	v_cvt_pk_bf16_f32 v106, v88, v89
	v_cvt_pk_bf16_f32 v107, v90, v91
	global_store_dwordx4 v109, v[92:95], s[8:9]
	global_store_dwordx4 v109, v[96:99], s[8:9] offset:16
	global_store_dwordx4 v109, v[100:103], s[8:9] offset:32
	global_store_dwordx4 v109, v[104:107], s[8:9] offset:48

; #define LAS __attribute__((address_space(3)))
; template <class T, class P> __device__ __forceinline__ T gld_nt(P p) { return __builtin_nontemporal_load((GAS const T*)p); }
; __device__ __forceinline__ unsigned pk2(float lo, float hi) { return pg8::cvt_pk_bf16(lo, hi); }
; __device__ __forceinline__ void tr_item64(const float* W, int N, int K, int src_a, int src_b, const float* g, bf16_t* WT, int dst_row0, int k0, LAS float* scr, int lane) {
;     const int sc = (lane < 32 ? src_a : src_b) + (lane & 31);
;     float v[64];
; #pragma unroll
;     for (int kk = 0; kk < 64; ++kk) v[kk] = gld_nt<float>(W + (size_t)(k0 + kk) * N + sc);
; #pragma unroll
;     for (int kk = 0; kk < 64; ++kk) scr[kk * 65 + lane] = g ? v[kk] * gld<float>(g + k0 + kk) : v[kk];
;     asm volatile("s_waitcnt lgkmcnt(0)" ::: "memory");
;     const int c = lane & 7;
; #pragma unroll
;     for (int j = 0; j < 8; ++j) { const int n = (lane >> 3) + 8 * j; const LAS float* sp = scr + (8 * c) * 65 + n;
;         u32x4 o; o.x = pk2(sp[0 * 65], sp[1 * 65]); o.y = pk2(sp[2 * 65], sp[3 * 65]); o.z = pk2(sp[4 * 65], sp[5 * 65]); o.w = pk2(sp[6 * 65], sp[7 * 65]);
;         gst<u32x4>(WT + (size_t)(dst_row0 + n) * K + k0 + 8 * c, o); }
;     asm volatile("s_waitcnt lgkmcnt(0)" ::: "memory");
; }
; __device__ __forceinline__ void p0_phase(LAS unsigned char* lds, const Args& a, const int w0) {
;     ...
;         if (r < 2 * I_SQ) { const int which = r / I_SQ; r %= I_SQ; const int L = r / 256, q = r % 256, nb = q & 15, kb = q >> 4;
;             tr_item64(a.in[which ? 12 : 11] + (size_t)L * DM * DM, DM, DM, nb * 64, nb * 64 + 32, nullptr, (bf16_t*)(ws + (which ? WS_WPG : WS_WOUT)) + (size_t)L * DM * DM, nb * 64, kb * 64, scr, lane); continue; }
.Ldp_a_skip:
	s_cmp_lt_u32 s40, 64
	s_cbranch_scc1 .Ldw_w_end
	v_readlane_b32 s14, v255, 36
	s_load_dwordx4 s[16:19], s[0:1], 0x58
	s_load_dwordx2 s[26:27], s[0:1], 0x68
	s_load_dwordx2 s[28:29], s[0:1], 0x80
	s_lshr_b32 s15, s40, 6
	s_add_i32 s15, s15, -1
	s_mul_i32 s12, s46, 7
	s_add_i32 s15, s15, s12
	v_mbcnt_lo_u32_b32 v54, -1, 0
	v_mbcnt_hi_u32_b32 v54, -1, v54
	s_waitcnt lgkmcnt(0)
	s_cmp_gt_u32 s15, 511
	s_cbranch_scc1 .Ldw_w_notout
	s_lshl_b32 s12, s14, 22
	s_add_u32 s8, s16, s12
	s_addc_u32 s9, s17, 0
	s_lshl_b32 s12, s14, 21
	s_add_u32 s12, s12, 0x1c00000
	s_add_u32 s12, s28, s12
	s_addc_u32 s13, s29, 0
	s_branch .Ldw_w_sq
.Ldw_w_notout:
	s_cmp_gt_u32 s15, 1023
	s_cbranch_scc1 .Ldw_w_pp
	s_add_i32 s15, s15, 0xfffffe00
	s_lshl_b32 s12, s14, 22
	s_add_u32 s8, s18, s12
	s_addc_u32 s9, s19, 0
	s_lshl_b32 s12, s14, 21
	s_add_u32 s12, s12, 0x2400000
	s_add_u32 s12, s28, s12
	s_addc_u32 s13, s29, 0
.Ldw_w_sq:
	s_and_b32 s10, s15, 15
	s_lshr_b32 s11, s15, 4
	s_lshl_b32 s11, s11, 17
	s_add_u32 s8, s8, s11
	s_addc_u32 s9, s9, 0
	s_lshl_b32 s11, s10, 8
	s_add_u32 s8, s8, s11
	s_addc_u32 s9, s9, 0
	s_lshl_b32 s10, s10, 17
	s_add_u32 s12, s12, s10
	s_addc_u32 s13, s13, 0
	s_lshr_b32 s11, s15, 4
	s_lshl_b32 s11, s11, 6
	s_add_u32 s12, s12, s11
	s_addc_u32 s13, s13, 0
	v_lshlrev_b32_e32 v52, 2, v54
	v_lshlrev_b32_e32 v53, 11, v54
	global_load_dword v4, v52, s[8:9] nt
	s_add_u32 s8, s8, 0x1000
	s_addc_u32 s9, s9, 0
	global_load_dword v5, v52, s[8:9] nt
	s_add_u32 s8, s8, 0x1000
	s_addc_u32 s9, s9, 0
	global_load_dword v6, v52, s[8:9] nt
	s_add_u32 s8, s8, 0x1000
	s_addc_u32 s9, s9, 0
	global_load_dword v7, v52, s[8:9] nt
	s_add_u32 s8, s8, 0x1000
	s_addc_u32 s9, s9, 0
	global_load_dword v8, v52, s[8:9] nt
	s_add_u32 s8, s8, 0x1000
	s_addc_u32 s9, s9, 0
	global_load_dword v9, v52, s[8:9] nt
	s_add_u32 s8, s8, 0x1000
	s_addc_u32 s9, s9, 0
	global_load_dword v10, v52, s[8:9] nt
	s_add_u32 s8, s8, 0x1000
	s_addc_u32 s9, s9, 0
	global_load_dword v11, v52, s[8:9] nt
	s_add_u32 s8, s8, 0x1000
	s_addc_u32 s9, s9, 0
	global_load_dword v12, v52, s[8:9] nt
	s_add_u32 s8, s8, 0x1000
	s_addc_u32 s9, s9, 0
	global_load_dword v13, v52, s[8:9] nt
	s_add_u32 s8, s8, 0x1000
	s_addc_u32 s9, s9, 0
	global_load_dword v14, v52, s[8:9] nt
	s_add_u32 s8, s8, 0x1000
	s_addc_u32 s9, s9, 0
	global_load_dword v15, v52, s[8:9] nt
	s_add_u32 s8, s8, 0x1000
	s_addc_u32 s9, s9, 0
	global_load_dword v16, v52, s[8:9] nt
	s_add_u32 s8, s8, 0x1000
	s_addc_u32 s9, s9, 0
	global_load_dword v17, v52, s[8:9] nt
	s_add_u32 s8, s8, 0x1000
	s_addc_u32 s9, s9, 0
	global_load_dword v18, v52, s[8:9] nt
	s_add_u32 s8, s8, 0x1000
	s_addc_u32 s9, s9, 0
	global_load_dword v19, v52, s[8:9] nt
	s_add_u32 s8, s8, 0x1000
	s_addc_u32 s9, s9, 0
	global_load_dword v20, v52, s[8:9] nt
	s_add_u32 s8, s8, 0x1000
	s_addc_u32 s9, s9, 0
	global_load_dword v21, v52, s[8:9] nt
	s_add_u32 s8, s8, 0x1000
	s_addc_u32 s9, s9, 0
	global_load_dword v22, v52, s[8:9] nt
	s_add_u32 s8, s8, 0x1000
	s_addc_u32 s9, s9, 0
	global_load_dword v23, v52, s[8:9] nt
	s_add_u32 s8, s8, 0x1000
	s_addc_u32 s9, s9, 0
	global_load_dword v24, v52, s[8:9] nt
	s_add_u32 s8, s8, 0x1000
	s_addc_u32 s9, s9, 0
	global_load_dword v25, v52, s[8:9] nt
	s_add_u32 s8, s8, 0x1000
	s_addc_u32 s9, s9, 0
	global_load_dword v26, v52, s[8:9] nt
	s_add_u32 s8, s8, 0x1000
	s_addc_u32 s9, s9, 0
	global_load_dword v27, v52, s[8:9] nt
	s_add_u32 s8, s8, 0x1000
	s_addc_u32 s9, s9, 0
	global_load_dword v28, v52, s[8:9] nt
	s_add_u32 s8, s8, 0x1000
	s_addc_u32 s9, s9, 0
	global_load_dword v29, v52, s[8:9] nt
	s_add_u32 s8, s8, 0x1000
	s_addc_u32 s9, s9, 0
	global_load_dword v30, v52, s[8:9] nt
	s_add_u32 s8, s8, 0x1000
	s_addc_u32 s9, s9, 0
	global_load_dword v31, v52, s[8:9] nt
	s_add_u32 s8, s8, 0x1000
	s_addc_u32 s9, s9, 0
	global_load_dword v32, v52, s[8:9] nt
	s_add_u32 s8, s8, 0x1000
	s_addc_u32 s9, s9, 0
	global_load_dword v33, v52, s[8:9] nt
	s_add_u32 s8, s8, 0x1000
	s_addc_u32 s9, s9, 0
	global_load_dword v34, v52, s[8:9] nt
	s_add_u32 s8, s8, 0x1000
	s_addc_u32 s9, s9, 0
	global_load_dword v35, v52, s[8:9] nt
	s_waitcnt vmcnt(24)
	v_cvt_pk_bf16_f32 v36, v4, v5
	v_cvt_pk_bf16_f32 v37, v6, v7
	v_cvt_pk_bf16_f32 v38, v8, v9
	v_cvt_pk_bf16_f32 v39, v10, v11
	s_waitcnt vmcnt(16)
	v_cvt_pk_bf16_f32 v40, v12, v13
	v_cvt_pk_bf16_f32 v41, v14, v15
	v_cvt_pk_bf16_f32 v42, v16, v17
	v_cvt_pk_bf16_f32 v43, v18, v19
	s_waitcnt vmcnt(8)
	v_cvt_pk_bf16_f32 v44, v20, v21
	v_cvt_pk_bf16_f32 v45, v22, v23
	v_cvt_pk_bf16_f32 v46, v24, v25
	v_cvt_pk_bf16_f32 v47, v26, v27
	s_waitcnt vmcnt(0)
	v_cvt_pk_bf16_f32 v48, v28, v29
	v_cvt_pk_bf16_f32 v49, v30, v31
	v_cvt_pk_bf16_f32 v50, v32, v33
	v_cvt_pk_bf16_f32 v51, v34, v35
	global_store_dwordx4 v53, v[36:39], s[12:13]
	global_store_dwordx4 v53, v[40:43], s[12:13] offset:16
	global_store_dwordx4 v53, v[44:47], s[12:13] offset:32
	global_store_dwordx4 v53, v[48:51], s[12:13] offset:48
	s_branch .Ldw_w_end
; #define LAS __attribute__((address_space(3)))
; template <class T, class P> __device__ __forceinline__ T gld_nt(P p) { return __builtin_nontemporal_load((GAS const T*)p); }
; __device__ __forceinline__ unsigned pk2(float lo, float hi) { return pg8::cvt_pk_bf16(lo, hi); }
; __device__ __forceinline__ void tr_item64(const float* W, int N, int K, int src_a, int src_b, const float* g, bf16_t* WT, int dst_row0, int k0, LAS float* scr, int lane) {
;     const int sc = (lane < 32 ? src_a : src_b) + (lane & 31);
;     float v[64];
; #pragma unroll
;     for (int kk = 0; kk < 64; ++kk) v[kk] = gld_nt<float>(W + (size_t)(k0 + kk) * N + sc);
; #pragma unroll
;     for (int kk = 0; kk < 64; ++kk) scr[kk * 65 + lane] = g ? v[kk] * gld<float>(g + k0 + kk) : v[kk];
;     asm volatile("s_waitcnt lgkmcnt(0)" ::: "memory");
;     const int c = lane & 7;
; #pragma unroll
;     for (int j = 0; j < 8; ++j) { const int n = (lane >> 3) + 8 * j; const LAS float* sp = scr + (8 * c) * 65 + n;
;         u32x4 o; o.x = pk2(sp[0 * 65], sp[1 * 65]); o.y = pk2(sp[2 * 65], sp[3 * 65]); o.z = pk2(sp[4 * 65], sp[5 * 65]); o.w = pk2(sp[6 * 65], sp[7 * 65]);
;         gst<u32x4>(WT + (size_t)(dst_row0 + n) * K + k0 + 8 * c, o); }
;     asm volatile("s_waitcnt lgkmcnt(0)" ::: "memory");
; }
; __device__ __forceinline__ void p0_phase(LAS unsigned char* lds, const Args& a, const int w0) {
;     ...
;         { const int L = r / 64, q = r % 64, nb = q & 15, kb = q >> 4;
;             tr_item64(a.in[13] + (size_t)L * PLE * DM, DM, PLE, nb * 64, nb * 64 + 32, nullptr, (bf16_t*)(ws + WS_WPP) + (size_t)L * DM * PLE, nb * 64, kb * 64, scr, lane); }
.Ldw_w_pp:
	s_cmp_gt_u32 s15, 1151
	s_cbranch_scc1 .Ldw_w_end
	s_cmp_gt_u32 s14, 2
	s_cbranch_scc1 .Ldw_w_end
	s_add_i32 s15, s15, 0xfffffc00
	s_add_i32 s14, s14, 1
	s_lshl_b32 s12, s14, 20
	s_add_u32 s8, s26, s12
	s_addc_u32 s9, s27, 0
	s_lshl_b32 s12, s14, 19
	s_add_u32 s12, s12, 0x2c00000
	s_add_u32 s12, s28, s12
	s_addc_u32 s13, s29, 0
	s_and_b32 s10, s15, 15
	s_lshr_b32 s11, s15, 4
	s_lshl_b32 s11, s11, 17
	s_add_u32 s8, s8, s11
	s_addc_u32 s9, s9, 0
	s_lshl_b32 s11, s10, 8
	s_add_u32 s8, s8, s11
	s_addc_u32 s9, s9, 0
	s_lshl_b32 s10, s10, 15
	s_add_u32 s12, s12, s10
	s_addc_u32 s13, s13, 0
	s_lshr_b32 s11, s15, 4
	s_lshl_b32 s11, s11, 6
	s_add_u32 s12, s12, s11
	s_addc_u32 s13, s13, 0
	v_lshlrev_b32_e32 v52, 2, v54
	v_lshlrev_b32_e32 v53, 9, v54
	global_load_dword v4, v52, s[8:9] nt
	s_add_u32 s8, s8, 0x1000
	s_addc_u32 s9, s9, 0
	global_load_dword v5, v52, s[8:9] nt
	s_add_u32 s8, s8, 0x1000
	s_addc_u32 s9, s9, 0
	global_load_dword v6, v52, s[8:9] nt
	s_add_u32 s8, s8, 0x1000
	s_addc_u32 s9, s9, 0
	global_load_dword v7, v52, s[8:9] nt
	s_add_u32 s8, s8, 0x1000
	s_addc_u32 s9, s9, 0
	global_load_dword v8, v52, s[8:9] nt
	s_add_u32 s8, s8, 0x1000
	s_addc_u32 s9, s9, 0
	global_load_dword v9, v52, s[8:9] nt
	s_add_u32 s8, s8, 0x1000
	s_addc_u32 s9, s9, 0
	global_load_dword v10, v52, s[8:9] nt
	s_add_u32 s8, s8, 0x1000
	s_addc_u32 s9, s9, 0
	global_load_dword v11, v52, s[8:9] nt
	s_add_u32 s8, s8, 0x1000
	s_addc_u32 s9, s9, 0
	global_load_dword v12, v52, s[8:9] nt
	s_add_u32 s8, s8, 0x1000
	s_addc_u32 s9, s9, 0
	global_load_dword v13, v52, s[8:9] nt
	s_add_u32 s8, s8, 0x1000
	s_addc_u32 s9, s9, 0
	global_load_dword v14, v52, s[8:9] nt
	s_add_u32 s8, s8, 0x1000
	s_addc_u32 s9, s9, 0
	global_load_dword v15, v52, s[8:9] nt
	s_add_u32 s8, s8, 0x1000
	s_addc_u32 s9, s9, 0
	global_load_dword v16, v52, s[8:9] nt
	s_add_u32 s8, s8, 0x1000
	s_addc_u32 s9, s9, 0
	global_load_dword v17, v52, s[8:9] nt
	s_add_u32 s8, s8, 0x1000
	s_addc_u32 s9, s9, 0
	global_load_dword v18, v52, s[8:9] nt
	s_add_u32 s8, s8, 0x1000
	s_addc_u32 s9, s9, 0
	global_load_dword v19, v52, s[8:9] nt
	s_add_u32 s8, s8, 0x1000
	s_addc_u32 s9, s9, 0
	global_load_dword v20, v52, s[8:9] nt
	s_add_u32 s8, s8, 0x1000
	s_addc_u32 s9, s9, 0
	global_load_dword v21, v52, s[8:9] nt
	s_add_u32 s8, s8, 0x1000
	s_addc_u32 s9, s9, 0
	global_load_dword v22, v52, s[8:9] nt
	s_add_u32 s8, s8, 0x1000
	s_addc_u32 s9, s9, 0
	global_load_dword v23, v52, s[8:9] nt
	s_add_u32 s8, s8, 0x1000
	s_addc_u32 s9, s9, 0
	global_load_dword v24, v52, s[8:9] nt
	s_add_u32 s8, s8, 0x1000
	s_addc_u32 s9, s9, 0
	global_load_dword v25, v52, s[8:9] nt
	s_add_u32 s8, s8, 0x1000
	s_addc_u32 s9, s9, 0
	global_load_dword v26, v52, s[8:9] nt
	s_add_u32 s8, s8, 0x1000
	s_addc_u32 s9, s9, 0
	global_load_dword v27, v52, s[8:9] nt
	s_add_u32 s8, s8, 0x1000
	s_addc_u32 s9, s9, 0
	global_load_dword v28, v52, s[8:9] nt
	s_add_u32 s8, s8, 0x1000
	s_addc_u32 s9, s9, 0
	global_load_dword v29, v52, s[8:9] nt
	s_add_u32 s8, s8, 0x1000
	s_addc_u32 s9, s9, 0
	global_load_dword v30, v52, s[8:9] nt
	s_add_u32 s8, s8, 0x1000
	s_addc_u32 s9, s9, 0
	global_load_dword v31, v52, s[8:9] nt
	s_add_u32 s8, s8, 0x1000
	s_addc_u32 s9, s9, 0
	global_load_dword v32, v52, s[8:9] nt
	s_add_u32 s8, s8, 0x1000
	s_addc_u32 s9, s9, 0
	global_load_dword v33, v52, s[8:9] nt
	s_add_u32 s8, s8, 0x1000
	s_addc_u32 s9, s9, 0
	global_load_dword v34, v52, s[8:9] nt
	s_add_u32 s8, s8, 0x1000
	s_addc_u32 s9, s9, 0
	global_load_dword v35, v52, s[8:9] nt
	s_waitcnt vmcnt(24)
	v_cvt_pk_bf16_f32 v36, v4, v5
	v_cvt_pk_bf16_f32 v37, v6, v7
	v_cvt_pk_bf16_f32 v38, v8, v9
	v_cvt_pk_bf16_f32 v39, v10, v11
	s_waitcnt vmcnt(16)
	v_cvt_pk_bf16_f32 v40, v12, v13
	v_cvt_pk_bf16_f32 v41, v14, v15
	v_cvt_pk_bf16_f32 v42, v16, v17
	v_cvt_pk_bf16_f32 v43, v18, v19
	s_waitcnt vmcnt(8)
	v_cvt_pk_bf16_f32 v44, v20, v21
	v_cvt_pk_bf16_f32 v45, v22, v23
	v_cvt_pk_bf16_f32 v46, v24, v25
	v_cvt_pk_bf16_f32 v47, v26, v27
	s_waitcnt vmcnt(0)
	v_cvt_pk_bf16_f32 v48, v28, v29
	v_cvt_pk_bf16_f32 v49, v30, v31
	v_cvt_pk_bf16_f32 v50, v32, v33
	v_cvt_pk_bf16_f32 v51, v34, v35
	global_store_dwordx4 v53, v[36:39], s[12:13]
	global_store_dwordx4 v53, v[40:43], s[12:13] offset:16
	global_store_dwordx4 v53, v[44:47], s[12:13] offset:32
	global_store_dwordx4 v53, v[48:51], s[12:13] offset:48
